# GEMM epilogue stores (in-projection and out-projection) write-through (sc1); barrier protocol unchanged (L2 write-back kept at every seam), on top of v11
# speedup vs baseline: 1.0193x; 1.0034x over previous
.LBB0_485:
	v_lshl_add_u32 v148, s64, 8, v164
	v_lshl_or_b32 v146, s22, 8, v166
	v_mul_lo_u32 v147, v148, s6
	v_lshlrev_b32_e32 v158, 6, v148
	v_add_u32_e32 v147, v147, v146
	s_cmp_lt_i32 s64, s72
	s_cselect_b32 s91, s5, s49
	s_cselect_b32 s90, s4, s48
	v_lshlrev_b32_e32 v146, 2, v147
	v_lshlrev_b32_e32 v147, 1, v147
	s_mov_b64 s[82:83], s[20:21]
	s_lshl_b32 s44, s6, 5
	s_mul_i32 s45, s44, 5
	s_and_b64 vcc, exec, s[68:69]
	s_cbranch_vccnz .Lepr_bf16
	s_lshl_b32 s42, s6, 6
	s_mul_i32 s43, s42, 5
	s_lshl_b32 s0, s22, 4
	s_lshl_b32 s1, s17, 2
	s_add_i32 s0, s0, s1
	s_add_u32 s64, s50, s0
	s_addc_u32 s65, s51, 0
	global_load_dwordx4 v[128:131], v146, s[90:91]
	global_load_dwordx4 v[132:135], v146, s[90:91] offset:16
	global_load_dwordx4 v[148:151], v146, s[90:91] offset:512
	global_load_dwordx4 v[160:163], v146, s[90:91] offset:528
	s_add_u32 s90, s90, s42
	s_addc_u32 s91, s91, 0
	global_load_dwordx4 v[168:171], v146, s[90:91]
	global_load_dwordx4 v[172:175], v146, s[90:91] offset:16
	global_load_dwordx4 v[176:179], v146, s[90:91] offset:512
	global_load_dwordx4 v[194:197], v146, s[90:91] offset:528
	s_add_u32 s90, s90, s42
	s_addc_u32 s91, s91, 0
	global_load_dwordx4 v[202:205], v146, s[90:91]
	global_load_dwordx4 v[206:209], v146, s[90:91] offset:16
	global_load_dwordx4 v[210:213], v146, s[90:91] offset:512
	global_load_dwordx4 v[214:217], v146, s[90:91] offset:528
	s_add_u32 s90, s90, s42
	s_addc_u32 s91, s91, 0
	global_load_dwordx4 v[218:221], v146, s[90:91]
	global_load_dwordx4 v[222:225], v146, s[90:91] offset:16
	global_load_dwordx4 v[226:229], v146, s[90:91] offset:512
	global_load_dwordx4 v[230:233], v146, s[90:91] offset:528
	s_add_u32 s90, s90, s43
	s_addc_u32 s91, s91, 0
	v_xor_b32_e32 v159, 16, v199
	v_xor_b32_e32 v180, 32, v199
	v_lshlrev_b32_e32 v159, 2, v159
	v_lshlrev_b32_e32 v180, 2, v180
	s_waitcnt vmcnt(12)
	v_pk_add_f32 v[124:125], v[124:125], v[128:129]
	v_pk_add_f32 v[126:127], v[126:127], v[130:131]
	v_pk_add_f32 v[120:121], v[120:121], v[132:133]
	v_pk_add_f32 v[122:123], v[122:123], v[134:135]
	v_mul_f32_e32 v132, v125, v125
	v_mul_f32_e32 v133, v127, v127
	v_mul_f32_e32 v134, v121, v121
	v_mul_f32_e32 v135, v123, v123
	v_fmac_f32_e32 v132, v124, v124
	v_fmac_f32_e32 v133, v126, v126
	v_fmac_f32_e32 v134, v120, v120
	v_fmac_f32_e32 v135, v122, v122
	v_cvt_pk_bf16_f32 v128, v124, v125
	v_cvt_pk_bf16_f32 v129, v126, v127
	v_cvt_pk_bf16_f32 v130, v120, v121
	v_cvt_pk_bf16_f32 v131, v122, v123
	v_add_f32_e32 v132, v132, v133
	v_add_f32_e32 v134, v134, v135
	global_store_dwordx4 v147, v[128:131], s[82:83] sc1
	v_add_f32_e32 v132, v132, v134
	v_pk_add_f32 v[116:117], v[116:117], v[148:149]
	v_pk_add_f32 v[118:119], v[118:119], v[150:151]
	v_pk_add_f32 v[112:113], v[112:113], v[160:161]
	v_pk_add_f32 v[114:115], v[114:115], v[162:163]
	v_mul_f32_e32 v160, v117, v117
	v_mul_f32_e32 v161, v119, v119
	v_mul_f32_e32 v162, v113, v113
	v_mul_f32_e32 v163, v115, v115
	v_fmac_f32_e32 v160, v116, v116
	v_fmac_f32_e32 v161, v118, v118
	v_fmac_f32_e32 v162, v112, v112
	v_fmac_f32_e32 v163, v114, v114
	v_cvt_pk_bf16_f32 v148, v116, v117
	v_cvt_pk_bf16_f32 v149, v118, v119
	v_cvt_pk_bf16_f32 v150, v112, v113
	v_cvt_pk_bf16_f32 v151, v114, v115
	v_add_f32_e32 v160, v160, v161
	v_add_f32_e32 v162, v162, v163
	global_store_dwordx4 v147, v[148:151], s[82:83] offset:256 sc1
	v_add_f32_e32 v160, v160, v162
	v_add_f32_e32 v132, v132, v160
	s_add_u32 s82, s82, s44
	s_addc_u32 s83, s83, 0
	global_load_dwordx4 v[124:127], v146, s[90:91]
	global_load_dwordx4 v[120:123], v146, s[90:91] offset:16
	global_load_dwordx4 v[116:119], v146, s[90:91] offset:512
	global_load_dwordx4 v[112:115], v146, s[90:91] offset:528
	s_add_u32 s90, s90, s42
	s_addc_u32 s91, s91, 0
	s_waitcnt vmcnt(14)
	v_pk_add_f32 v[108:109], v[108:109], v[168:169]
	v_pk_add_f32 v[110:111], v[110:111], v[170:171]
	v_pk_add_f32 v[104:105], v[104:105], v[172:173]
	v_pk_add_f32 v[106:107], v[106:107], v[174:175]
	v_mul_f32_e32 v172, v109, v109
	v_mul_f32_e32 v173, v111, v111
	v_mul_f32_e32 v174, v105, v105
	v_mul_f32_e32 v175, v107, v107
	v_fmac_f32_e32 v172, v108, v108
	v_fmac_f32_e32 v173, v110, v110
	v_fmac_f32_e32 v174, v104, v104
	v_fmac_f32_e32 v175, v106, v106
	v_cvt_pk_bf16_f32 v168, v108, v109
	v_cvt_pk_bf16_f32 v169, v110, v111
	v_cvt_pk_bf16_f32 v170, v104, v105
	v_cvt_pk_bf16_f32 v171, v106, v107
	v_add_f32_e32 v172, v172, v173
	v_add_f32_e32 v174, v174, v175
	global_store_dwordx4 v147, v[168:171], s[82:83] sc1
	v_add_f32_e32 v172, v172, v174
	v_pk_add_f32 v[100:101], v[100:101], v[176:177]
	v_pk_add_f32 v[102:103], v[102:103], v[178:179]
	v_pk_add_f32 v[96:97], v[96:97], v[194:195]
	v_pk_add_f32 v[98:99], v[98:99], v[196:197]
	v_mul_f32_e32 v194, v101, v101
	v_mul_f32_e32 v195, v103, v103
	v_mul_f32_e32 v196, v97, v97
	v_mul_f32_e32 v197, v99, v99
	v_fmac_f32_e32 v194, v100, v100
	v_fmac_f32_e32 v195, v102, v102
	v_fmac_f32_e32 v196, v96, v96
	v_fmac_f32_e32 v197, v98, v98
	v_cvt_pk_bf16_f32 v176, v100, v101
	v_cvt_pk_bf16_f32 v177, v102, v103
	v_cvt_pk_bf16_f32 v178, v96, v97
	v_cvt_pk_bf16_f32 v179, v98, v99
	v_add_f32_e32 v194, v194, v195
	v_add_f32_e32 v196, v196, v197
	global_store_dwordx4 v147, v[176:179], s[82:83] offset:256 sc1
	v_add_f32_e32 v194, v194, v196
	v_add_f32_e32 v172, v172, v194
	s_add_u32 s82, s82, s44
	s_addc_u32 s83, s83, 0
	global_load_dwordx4 v[108:111], v146, s[90:91]
	global_load_dwordx4 v[104:107], v146, s[90:91] offset:16
	global_load_dwordx4 v[100:103], v146, s[90:91] offset:512
	global_load_dwordx4 v[96:99], v146, s[90:91] offset:528
	s_add_u32 s90, s90, s42
	s_addc_u32 s91, s91, 0
	s_waitcnt vmcnt(16)
	v_pk_add_f32 v[92:93], v[92:93], v[202:203]
	v_pk_add_f32 v[94:95], v[94:95], v[204:205]
	v_pk_add_f32 v[88:89], v[88:89], v[206:207]
	v_pk_add_f32 v[90:91], v[90:91], v[208:209]
	v_mul_f32_e32 v206, v93, v93
	v_mul_f32_e32 v207, v95, v95
	v_mul_f32_e32 v208, v89, v89
	v_mul_f32_e32 v209, v91, v91
	v_fmac_f32_e32 v206, v92, v92
	v_fmac_f32_e32 v207, v94, v94
	v_fmac_f32_e32 v208, v88, v88
	v_fmac_f32_e32 v209, v90, v90
	v_cvt_pk_bf16_f32 v202, v92, v93
	v_cvt_pk_bf16_f32 v203, v94, v95
	v_cvt_pk_bf16_f32 v204, v88, v89
	v_cvt_pk_bf16_f32 v205, v90, v91
	v_add_f32_e32 v206, v206, v207
	v_add_f32_e32 v208, v208, v209
	global_store_dwordx4 v147, v[202:205], s[82:83] sc1
	v_add_f32_e32 v206, v206, v208
	v_pk_add_f32 v[84:85], v[84:85], v[210:211]
	v_pk_add_f32 v[86:87], v[86:87], v[212:213]
	v_pk_add_f32 v[80:81], v[80:81], v[214:215]
	v_pk_add_f32 v[82:83], v[82:83], v[216:217]
	v_mul_f32_e32 v214, v85, v85
	v_mul_f32_e32 v215, v87, v87
	v_mul_f32_e32 v216, v81, v81
	v_mul_f32_e32 v217, v83, v83
	v_fmac_f32_e32 v214, v84, v84
	v_fmac_f32_e32 v215, v86, v86
	v_fmac_f32_e32 v216, v80, v80
	v_fmac_f32_e32 v217, v82, v82
	v_cvt_pk_bf16_f32 v210, v84, v85
	v_cvt_pk_bf16_f32 v211, v86, v87
	v_cvt_pk_bf16_f32 v212, v80, v81
	v_cvt_pk_bf16_f32 v213, v82, v83
	v_add_f32_e32 v214, v214, v215
	v_add_f32_e32 v216, v216, v217
	global_store_dwordx4 v147, v[210:213], s[82:83] offset:256 sc1
	v_add_f32_e32 v214, v214, v216
	v_add_f32_e32 v206, v206, v214
	s_add_u32 s82, s82, s44
	s_addc_u32 s83, s83, 0
	global_load_dwordx4 v[92:95], v146, s[90:91]
	global_load_dwordx4 v[88:91], v146, s[90:91] offset:16
	global_load_dwordx4 v[84:87], v146, s[90:91] offset:512
	global_load_dwordx4 v[80:83], v146, s[90:91] offset:528
	s_add_u32 s90, s90, s42
	s_addc_u32 s91, s91, 0
	s_waitcnt vmcnt(18)
	v_pk_add_f32 v[76:77], v[76:77], v[218:219]
	v_pk_add_f32 v[78:79], v[78:79], v[220:221]
	v_pk_add_f32 v[72:73], v[72:73], v[222:223]
	v_pk_add_f32 v[74:75], v[74:75], v[224:225]
	v_mul_f32_e32 v222, v77, v77
	v_mul_f32_e32 v223, v79, v79
	v_mul_f32_e32 v224, v73, v73
	v_mul_f32_e32 v225, v75, v75
	v_fmac_f32_e32 v222, v76, v76
	v_fmac_f32_e32 v223, v78, v78
	v_fmac_f32_e32 v224, v72, v72
	v_fmac_f32_e32 v225, v74, v74
	v_cvt_pk_bf16_f32 v218, v76, v77
	v_cvt_pk_bf16_f32 v219, v78, v79
	v_cvt_pk_bf16_f32 v220, v72, v73
	v_cvt_pk_bf16_f32 v221, v74, v75
	v_add_f32_e32 v222, v222, v223
	v_add_f32_e32 v224, v224, v225
	global_store_dwordx4 v147, v[218:221], s[82:83] sc1
	v_add_f32_e32 v222, v222, v224
	v_pk_add_f32 v[68:69], v[68:69], v[226:227]
	v_pk_add_f32 v[70:71], v[70:71], v[228:229]
	v_pk_add_f32 v[64:65], v[64:65], v[230:231]
	v_pk_add_f32 v[66:67], v[66:67], v[232:233]
	v_mul_f32_e32 v230, v69, v69
	v_mul_f32_e32 v231, v71, v71
	v_mul_f32_e32 v232, v65, v65
	v_mul_f32_e32 v233, v67, v67
	v_fmac_f32_e32 v230, v68, v68
	v_fmac_f32_e32 v231, v70, v70
	v_fmac_f32_e32 v232, v64, v64
	v_fmac_f32_e32 v233, v66, v66
	v_cvt_pk_bf16_f32 v226, v68, v69
	v_cvt_pk_bf16_f32 v227, v70, v71
	v_cvt_pk_bf16_f32 v228, v64, v65
	v_cvt_pk_bf16_f32 v229, v66, v67
	v_add_f32_e32 v230, v230, v231
	v_add_f32_e32 v232, v232, v233
	global_store_dwordx4 v147, v[226:229], s[82:83] offset:256 sc1
	v_add_f32_e32 v230, v230, v232
	v_add_f32_e32 v222, v222, v230
	s_add_u32 s82, s82, s45
	s_addc_u32 s83, s83, 0
	global_load_dwordx4 v[76:79], v146, s[90:91]
	global_load_dwordx4 v[72:75], v146, s[90:91] offset:16
	global_load_dwordx4 v[68:71], v146, s[90:91] offset:512
	global_load_dwordx4 v[64:67], v146, s[90:91] offset:528
	s_waitcnt vmcnt(18)
	v_pk_add_f32 v[60:61], v[60:61], v[124:125]
	v_pk_add_f32 v[62:63], v[62:63], v[126:127]
	v_pk_add_f32 v[56:57], v[56:57], v[120:121]
	v_pk_add_f32 v[58:59], v[58:59], v[122:123]
	v_mul_f32_e32 v120, v61, v61
	v_mul_f32_e32 v121, v63, v63
	v_mul_f32_e32 v122, v57, v57
	v_mul_f32_e32 v123, v59, v59
	v_fmac_f32_e32 v120, v60, v60
	v_fmac_f32_e32 v121, v62, v62
	v_fmac_f32_e32 v122, v56, v56
	v_fmac_f32_e32 v123, v58, v58
	v_cvt_pk_bf16_f32 v124, v60, v61
	v_cvt_pk_bf16_f32 v125, v62, v63
	v_cvt_pk_bf16_f32 v126, v56, v57
	v_cvt_pk_bf16_f32 v127, v58, v59
	v_add_f32_e32 v120, v120, v121
	v_add_f32_e32 v122, v122, v123
	global_store_dwordx4 v147, v[124:127], s[82:83] sc1
	v_add_f32_e32 v120, v120, v122
	v_pk_add_f32 v[52:53], v[52:53], v[116:117]
	v_pk_add_f32 v[54:55], v[54:55], v[118:119]
	v_pk_add_f32 v[48:49], v[48:49], v[112:113]
	v_pk_add_f32 v[50:51], v[50:51], v[114:115]
	v_mul_f32_e32 v112, v53, v53
	v_mul_f32_e32 v113, v55, v55
	v_mul_f32_e32 v114, v49, v49
	v_mul_f32_e32 v115, v51, v51
	v_fmac_f32_e32 v112, v52, v52
	v_fmac_f32_e32 v113, v54, v54
	v_fmac_f32_e32 v114, v48, v48
	v_fmac_f32_e32 v115, v50, v50
	v_cvt_pk_bf16_f32 v116, v52, v53
	v_cvt_pk_bf16_f32 v117, v54, v55
	v_cvt_pk_bf16_f32 v118, v48, v49
	v_cvt_pk_bf16_f32 v119, v50, v51
	v_add_f32_e32 v112, v112, v113
	v_add_f32_e32 v114, v114, v115
	global_store_dwordx4 v147, v[116:119], s[82:83] offset:256 sc1
	v_add_f32_e32 v112, v112, v114
	v_add_f32_e32 v120, v120, v112
	s_add_u32 s82, s82, s44
	s_addc_u32 s83, s83, 0
	s_waitcnt vmcnt(14)
	v_pk_add_f32 v[44:45], v[44:45], v[108:109]
	v_pk_add_f32 v[46:47], v[46:47], v[110:111]
	v_pk_add_f32 v[40:41], v[40:41], v[104:105]
	v_pk_add_f32 v[42:43], v[42:43], v[106:107]
	v_mul_f32_e32 v104, v45, v45
	v_mul_f32_e32 v105, v47, v47
	v_mul_f32_e32 v106, v41, v41
	v_mul_f32_e32 v107, v43, v43
	v_fmac_f32_e32 v104, v44, v44
	v_fmac_f32_e32 v105, v46, v46
	v_fmac_f32_e32 v106, v40, v40
	v_fmac_f32_e32 v107, v42, v42
	v_cvt_pk_bf16_f32 v108, v44, v45
	v_cvt_pk_bf16_f32 v109, v46, v47
	v_cvt_pk_bf16_f32 v110, v40, v41
	v_cvt_pk_bf16_f32 v111, v42, v43
	v_add_f32_e32 v104, v104, v105
	v_add_f32_e32 v106, v106, v107
	global_store_dwordx4 v147, v[108:111], s[82:83] sc1
	v_add_f32_e32 v104, v104, v106
	v_pk_add_f32 v[36:37], v[36:37], v[100:101]
	v_pk_add_f32 v[38:39], v[38:39], v[102:103]
	v_pk_add_f32 v[32:33], v[32:33], v[96:97]
	v_pk_add_f32 v[34:35], v[34:35], v[98:99]
	v_mul_f32_e32 v96, v37, v37
	v_mul_f32_e32 v97, v39, v39
	v_mul_f32_e32 v98, v33, v33
	v_mul_f32_e32 v99, v35, v35
	v_fmac_f32_e32 v96, v36, v36
	v_fmac_f32_e32 v97, v38, v38
	v_fmac_f32_e32 v98, v32, v32
	v_fmac_f32_e32 v99, v34, v34
	v_cvt_pk_bf16_f32 v100, v36, v37
	v_cvt_pk_bf16_f32 v101, v38, v39
	v_cvt_pk_bf16_f32 v102, v32, v33
	v_cvt_pk_bf16_f32 v103, v34, v35
	v_add_f32_e32 v96, v96, v97
	v_add_f32_e32 v98, v98, v99
	global_store_dwordx4 v147, v[100:103], s[82:83] offset:256 sc1
	v_add_f32_e32 v96, v96, v98
	v_add_f32_e32 v104, v104, v96
	s_add_u32 s82, s82, s44
	s_addc_u32 s83, s83, 0
	s_waitcnt vmcnt(10)
	v_pk_add_f32 v[28:29], v[28:29], v[92:93]
	v_pk_add_f32 v[30:31], v[30:31], v[94:95]
	v_pk_add_f32 v[24:25], v[24:25], v[88:89]
	v_pk_add_f32 v[26:27], v[26:27], v[90:91]
	v_mul_f32_e32 v88, v29, v29
	v_mul_f32_e32 v89, v31, v31
	v_mul_f32_e32 v90, v25, v25
	v_mul_f32_e32 v91, v27, v27
	v_fmac_f32_e32 v88, v28, v28
	v_fmac_f32_e32 v89, v30, v30
	v_fmac_f32_e32 v90, v24, v24
	v_fmac_f32_e32 v91, v26, v26
	v_cvt_pk_bf16_f32 v92, v28, v29
	v_cvt_pk_bf16_f32 v93, v30, v31
	v_cvt_pk_bf16_f32 v94, v24, v25
	v_cvt_pk_bf16_f32 v95, v26, v27
	v_add_f32_e32 v88, v88, v89
	v_add_f32_e32 v90, v90, v91
	global_store_dwordx4 v147, v[92:95], s[82:83] sc1
	v_add_f32_e32 v88, v88, v90
	v_pk_add_f32 v[20:21], v[20:21], v[84:85]
	v_pk_add_f32 v[22:23], v[22:23], v[86:87]
	v_pk_add_f32 v[16:17], v[16:17], v[80:81]
	v_pk_add_f32 v[18:19], v[18:19], v[82:83]
	v_mul_f32_e32 v80, v21, v21
	v_mul_f32_e32 v81, v23, v23
	v_mul_f32_e32 v82, v17, v17
	v_mul_f32_e32 v83, v19, v19
	v_fmac_f32_e32 v80, v20, v20
	v_fmac_f32_e32 v81, v22, v22
	v_fmac_f32_e32 v82, v16, v16
	v_fmac_f32_e32 v83, v18, v18
	v_cvt_pk_bf16_f32 v84, v20, v21
	v_cvt_pk_bf16_f32 v85, v22, v23
	v_cvt_pk_bf16_f32 v86, v16, v17
	v_cvt_pk_bf16_f32 v87, v18, v19
	v_add_f32_e32 v80, v80, v81
	v_add_f32_e32 v82, v82, v83
	global_store_dwordx4 v147, v[84:87], s[82:83] offset:256 sc1
	v_add_f32_e32 v80, v80, v82
	v_add_f32_e32 v88, v88, v80
	s_add_u32 s82, s82, s44
	s_addc_u32 s83, s83, 0
	s_waitcnt vmcnt(6)
	v_pk_add_f32 v[12:13], v[12:13], v[76:77]
	v_pk_add_f32 v[14:15], v[14:15], v[78:79]
	v_pk_add_f32 v[8:9], v[8:9], v[72:73]
	v_pk_add_f32 v[10:11], v[10:11], v[74:75]
	v_mul_f32_e32 v72, v13, v13
	v_mul_f32_e32 v73, v15, v15
	v_mul_f32_e32 v74, v9, v9
	v_mul_f32_e32 v75, v11, v11
	v_fmac_f32_e32 v72, v12, v12
	v_fmac_f32_e32 v73, v14, v14
	v_fmac_f32_e32 v74, v8, v8
	v_fmac_f32_e32 v75, v10, v10
	v_cvt_pk_bf16_f32 v76, v12, v13
	v_cvt_pk_bf16_f32 v77, v14, v15
	v_cvt_pk_bf16_f32 v78, v8, v9
	v_cvt_pk_bf16_f32 v79, v10, v11
	v_add_f32_e32 v72, v72, v73
	v_add_f32_e32 v74, v74, v75
	global_store_dwordx4 v147, v[76:79], s[82:83] sc1
	v_add_f32_e32 v72, v72, v74
	v_pk_add_f32 v[4:5], v[4:5], v[68:69]
	v_pk_add_f32 v[6:7], v[6:7], v[70:71]
	v_pk_add_f32 v[0:1], v[0:1], v[64:65]
	v_pk_add_f32 v[2:3], v[2:3], v[66:67]
	v_mul_f32_e32 v64, v5, v5
	v_mul_f32_e32 v65, v7, v7
	v_mul_f32_e32 v66, v1, v1
	v_mul_f32_e32 v67, v3, v3
	v_fmac_f32_e32 v64, v4, v4
	v_fmac_f32_e32 v65, v6, v6
	v_fmac_f32_e32 v66, v0, v0
	v_fmac_f32_e32 v67, v2, v2
	v_cvt_pk_bf16_f32 v68, v4, v5
	v_cvt_pk_bf16_f32 v69, v6, v7
	v_cvt_pk_bf16_f32 v70, v0, v1
	v_cvt_pk_bf16_f32 v71, v2, v3
	v_add_f32_e32 v64, v64, v65
	v_add_f32_e32 v66, v66, v67
	global_store_dwordx4 v147, v[68:71], s[82:83] offset:256 sc1
	v_add_f32_e32 v64, v64, v66
	v_add_f32_e32 v72, v72, v64
	ds_bpermute_b32 v161, v159, v132
	ds_bpermute_b32 v195, v159, v172
	ds_bpermute_b32 v215, v159, v206
	ds_bpermute_b32 v231, v159, v222
	ds_bpermute_b32 v113, v159, v120
	ds_bpermute_b32 v97, v159, v104
	ds_bpermute_b32 v81, v159, v88
	ds_bpermute_b32 v65, v159, v72
	s_waitcnt lgkmcnt(0)
	v_add_f32_e32 v132, v132, v161
	v_add_f32_e32 v172, v172, v195
	v_add_f32_e32 v206, v206, v215
	v_add_f32_e32 v222, v222, v231
	v_add_f32_e32 v120, v120, v113
	v_add_f32_e32 v104, v104, v97
	v_add_f32_e32 v88, v88, v81
	v_add_f32_e32 v72, v72, v65
	ds_bpermute_b32 v161, v180, v132
	ds_bpermute_b32 v195, v180, v172
	ds_bpermute_b32 v215, v180, v206
	ds_bpermute_b32 v231, v180, v222
	ds_bpermute_b32 v113, v180, v120
	ds_bpermute_b32 v97, v180, v104
	ds_bpermute_b32 v81, v180, v88
	ds_bpermute_b32 v65, v180, v72
	s_waitcnt lgkmcnt(0)
	v_add_f32_e32 v132, v132, v161
	v_add_f32_e32 v172, v172, v195
	v_add_f32_e32 v206, v206, v215
	v_add_f32_e32 v222, v222, v231
	v_add_f32_e32 v120, v120, v113
	v_add_f32_e32 v104, v104, v97
	v_add_f32_e32 v88, v88, v81
	v_add_f32_e32 v72, v72, v65
	s_and_saveexec_b64 s[0:1], s[38:39]
	global_store_dword v158, v132, s[64:65] sc1
	global_store_dword v158, v172, s[64:65] offset:1024 sc1
	global_store_dword v158, v206, s[64:65] offset:2048 sc1
	global_store_dword v158, v222, s[64:65] offset:3072 sc1
	s_add_u32 s64, s64, 0x2000
	s_addc_u32 s65, s65, 0
	global_store_dword v158, v120, s[64:65] sc1
	global_store_dword v158, v104, s[64:65] offset:1024 sc1
	global_store_dword v158, v88, s[64:65] offset:2048 sc1
	global_store_dword v158, v72, s[64:65] offset:3072 sc1
	s_or_b64 exec, exec, s[0:1]
	s_branch .LBB0_565
.Lepr_bf16:
	s_mov_b64 s[90:91], s[86:87]
	global_load_dwordx4 v[128:131], v147, s[90:91]
	global_load_dwordx4 v[132:135], v147, s[90:91] offset:256
	s_add_u32 s90, s90, s44
	s_addc_u32 s91, s91, 0
	global_load_dwordx4 v[148:151], v147, s[90:91]
	global_load_dwordx4 v[160:163], v147, s[90:91] offset:256
	s_add_u32 s90, s90, s44
	s_addc_u32 s91, s91, 0
	global_load_dwordx4 v[168:171], v147, s[90:91]
	global_load_dwordx4 v[172:175], v147, s[90:91] offset:256
	s_add_u32 s90, s90, s44
	s_addc_u32 s91, s91, 0
	global_load_dwordx4 v[176:179], v147, s[90:91]
	global_load_dwordx4 v[194:197], v147, s[90:91] offset:256
	s_add_u32 s90, s90, s45
	s_addc_u32 s91, s91, 0
	global_load_dwordx4 v[202:205], v147, s[90:91]
	global_load_dwordx4 v[206:209], v147, s[90:91] offset:256
	s_add_u32 s90, s90, s44
	s_addc_u32 s91, s91, 0
	global_load_dwordx4 v[210:213], v147, s[90:91]
	global_load_dwordx4 v[214:217], v147, s[90:91] offset:256
	s_add_u32 s90, s90, s44
	s_addc_u32 s91, s91, 0
	global_load_dwordx4 v[218:221], v147, s[90:91]
	global_load_dwordx4 v[222:225], v147, s[90:91] offset:256
	s_add_u32 s90, s90, s44
	s_addc_u32 s91, s91, 0
	global_load_dwordx4 v[226:229], v147, s[90:91]
	global_load_dwordx4 v[230:233], v147, s[90:91] offset:256
	s_waitcnt vmcnt(14)
	v_lshlrev_b32_e32 v234, 16, v128
	v_and_b32_e32 v235, 0xffff0000, v128
	v_lshlrev_b32_e32 v236, 16, v129
	v_and_b32_e32 v237, 0xffff0000, v129
	v_lshlrev_b32_e32 v238, 16, v130
	v_and_b32_e32 v239, 0xffff0000, v130
	v_lshlrev_b32_e32 v180, 16, v131
	v_and_b32_e32 v181, 0xffff0000, v131
	v_pk_add_f32 v[124:125], v[124:125], v[234:235]
	v_pk_add_f32 v[126:127], v[126:127], v[236:237]
	v_pk_add_f32 v[120:121], v[120:121], v[238:239]
	v_pk_add_f32 v[122:123], v[122:123], v[180:181]
	v_cvt_pk_bf16_f32 v128, v124, v125
	v_cvt_pk_bf16_f32 v129, v126, v127
	v_cvt_pk_bf16_f32 v130, v120, v121
	v_cvt_pk_bf16_f32 v131, v122, v123
	global_store_dwordx4 v147, v[128:131], s[82:83] sc1
	v_lshlrev_b32_e32 v234, 16, v132
	v_and_b32_e32 v235, 0xffff0000, v132
	v_lshlrev_b32_e32 v236, 16, v133
	v_and_b32_e32 v237, 0xffff0000, v133
	v_lshlrev_b32_e32 v238, 16, v134
	v_and_b32_e32 v239, 0xffff0000, v134
	v_lshlrev_b32_e32 v180, 16, v135
	v_and_b32_e32 v181, 0xffff0000, v135
	v_pk_add_f32 v[116:117], v[116:117], v[234:235]
	v_pk_add_f32 v[118:119], v[118:119], v[236:237]
	v_pk_add_f32 v[112:113], v[112:113], v[238:239]
	v_pk_add_f32 v[114:115], v[114:115], v[180:181]
	v_cvt_pk_bf16_f32 v132, v116, v117
	v_cvt_pk_bf16_f32 v133, v118, v119
	v_cvt_pk_bf16_f32 v134, v112, v113
	v_cvt_pk_bf16_f32 v135, v114, v115
	global_store_dwordx4 v147, v[132:135], s[82:83] offset:256 sc1
	s_add_u32 s82, s82, s44
	s_addc_u32 s83, s83, 0
	s_waitcnt vmcnt(14)
	v_lshlrev_b32_e32 v234, 16, v148
	v_and_b32_e32 v235, 0xffff0000, v148
	v_lshlrev_b32_e32 v236, 16, v149
	v_and_b32_e32 v237, 0xffff0000, v149
	v_lshlrev_b32_e32 v238, 16, v150
	v_and_b32_e32 v239, 0xffff0000, v150
	v_lshlrev_b32_e32 v180, 16, v151
	v_and_b32_e32 v181, 0xffff0000, v151
	v_pk_add_f32 v[108:109], v[108:109], v[234:235]
	v_pk_add_f32 v[110:111], v[110:111], v[236:237]
	v_pk_add_f32 v[104:105], v[104:105], v[238:239]
	v_pk_add_f32 v[106:107], v[106:107], v[180:181]
	v_cvt_pk_bf16_f32 v148, v108, v109
	v_cvt_pk_bf16_f32 v149, v110, v111
	v_cvt_pk_bf16_f32 v150, v104, v105
	v_cvt_pk_bf16_f32 v151, v106, v107
	global_store_dwordx4 v147, v[148:151], s[82:83] sc1
	v_lshlrev_b32_e32 v234, 16, v160
	v_and_b32_e32 v235, 0xffff0000, v160
	v_lshlrev_b32_e32 v236, 16, v161
	v_and_b32_e32 v237, 0xffff0000, v161
	v_lshlrev_b32_e32 v238, 16, v162
	v_and_b32_e32 v239, 0xffff0000, v162
	v_lshlrev_b32_e32 v180, 16, v163
	v_and_b32_e32 v181, 0xffff0000, v163
	v_pk_add_f32 v[100:101], v[100:101], v[234:235]
	v_pk_add_f32 v[102:103], v[102:103], v[236:237]
	v_pk_add_f32 v[96:97], v[96:97], v[238:239]
	v_pk_add_f32 v[98:99], v[98:99], v[180:181]
	v_cvt_pk_bf16_f32 v160, v100, v101
	v_cvt_pk_bf16_f32 v161, v102, v103
	v_cvt_pk_bf16_f32 v162, v96, v97
	v_cvt_pk_bf16_f32 v163, v98, v99
	global_store_dwordx4 v147, v[160:163], s[82:83] offset:256 sc1
	s_add_u32 s82, s82, s44
	s_addc_u32 s83, s83, 0
	s_waitcnt vmcnt(14)
	v_lshlrev_b32_e32 v234, 16, v168
	v_and_b32_e32 v235, 0xffff0000, v168
	v_lshlrev_b32_e32 v236, 16, v169
	v_and_b32_e32 v237, 0xffff0000, v169
	v_lshlrev_b32_e32 v238, 16, v170
	v_and_b32_e32 v239, 0xffff0000, v170
	v_lshlrev_b32_e32 v180, 16, v171
	v_and_b32_e32 v181, 0xffff0000, v171
	v_pk_add_f32 v[92:93], v[92:93], v[234:235]
	v_pk_add_f32 v[94:95], v[94:95], v[236:237]
	v_pk_add_f32 v[88:89], v[88:89], v[238:239]
	v_pk_add_f32 v[90:91], v[90:91], v[180:181]
	v_cvt_pk_bf16_f32 v168, v92, v93
	v_cvt_pk_bf16_f32 v169, v94, v95
	v_cvt_pk_bf16_f32 v170, v88, v89
	v_cvt_pk_bf16_f32 v171, v90, v91
	global_store_dwordx4 v147, v[168:171], s[82:83] sc1
	v_lshlrev_b32_e32 v234, 16, v172
	v_and_b32_e32 v235, 0xffff0000, v172
	v_lshlrev_b32_e32 v236, 16, v173
	v_and_b32_e32 v237, 0xffff0000, v173
	v_lshlrev_b32_e32 v238, 16, v174
	v_and_b32_e32 v239, 0xffff0000, v174
	v_lshlrev_b32_e32 v180, 16, v175
	v_and_b32_e32 v181, 0xffff0000, v175
	v_pk_add_f32 v[84:85], v[84:85], v[234:235]
	v_pk_add_f32 v[86:87], v[86:87], v[236:237]
	v_pk_add_f32 v[80:81], v[80:81], v[238:239]
	v_pk_add_f32 v[82:83], v[82:83], v[180:181]
	v_cvt_pk_bf16_f32 v172, v84, v85
	v_cvt_pk_bf16_f32 v173, v86, v87
	v_cvt_pk_bf16_f32 v174, v80, v81
	v_cvt_pk_bf16_f32 v175, v82, v83
	global_store_dwordx4 v147, v[172:175], s[82:83] offset:256 sc1
	s_add_u32 s82, s82, s44
	s_addc_u32 s83, s83, 0
	s_waitcnt vmcnt(14)
	v_lshlrev_b32_e32 v234, 16, v176
	v_and_b32_e32 v235, 0xffff0000, v176
	v_lshlrev_b32_e32 v236, 16, v177
	v_and_b32_e32 v237, 0xffff0000, v177
	v_lshlrev_b32_e32 v238, 16, v178
	v_and_b32_e32 v239, 0xffff0000, v178
	v_lshlrev_b32_e32 v180, 16, v179
	v_and_b32_e32 v181, 0xffff0000, v179
	v_pk_add_f32 v[76:77], v[76:77], v[234:235]
	v_pk_add_f32 v[78:79], v[78:79], v[236:237]
	v_pk_add_f32 v[72:73], v[72:73], v[238:239]
	v_pk_add_f32 v[74:75], v[74:75], v[180:181]
	v_cvt_pk_bf16_f32 v176, v76, v77
	v_cvt_pk_bf16_f32 v177, v78, v79
	v_cvt_pk_bf16_f32 v178, v72, v73
	v_cvt_pk_bf16_f32 v179, v74, v75
	global_store_dwordx4 v147, v[176:179], s[82:83] sc1
	v_lshlrev_b32_e32 v234, 16, v194
	v_and_b32_e32 v235, 0xffff0000, v194
	v_lshlrev_b32_e32 v236, 16, v195
	v_and_b32_e32 v237, 0xffff0000, v195
	v_lshlrev_b32_e32 v238, 16, v196
	v_and_b32_e32 v239, 0xffff0000, v196
	v_lshlrev_b32_e32 v180, 16, v197
	v_and_b32_e32 v181, 0xffff0000, v197
	v_pk_add_f32 v[68:69], v[68:69], v[234:235]
	v_pk_add_f32 v[70:71], v[70:71], v[236:237]
	v_pk_add_f32 v[64:65], v[64:65], v[238:239]
	v_pk_add_f32 v[66:67], v[66:67], v[180:181]
	v_cvt_pk_bf16_f32 v194, v68, v69
	v_cvt_pk_bf16_f32 v195, v70, v71
	v_cvt_pk_bf16_f32 v196, v64, v65
	v_cvt_pk_bf16_f32 v197, v66, v67
	global_store_dwordx4 v147, v[194:197], s[82:83] offset:256 sc1
	s_add_u32 s82, s82, s45
	s_addc_u32 s83, s83, 0
	s_waitcnt vmcnt(14)
	v_lshlrev_b32_e32 v234, 16, v202
	v_and_b32_e32 v235, 0xffff0000, v202
	v_lshlrev_b32_e32 v236, 16, v203
	v_and_b32_e32 v237, 0xffff0000, v203
	v_lshlrev_b32_e32 v238, 16, v204
	v_and_b32_e32 v239, 0xffff0000, v204
	v_lshlrev_b32_e32 v180, 16, v205
	v_and_b32_e32 v181, 0xffff0000, v205
	v_pk_add_f32 v[60:61], v[60:61], v[234:235]
	v_pk_add_f32 v[62:63], v[62:63], v[236:237]
	v_pk_add_f32 v[56:57], v[56:57], v[238:239]
	v_pk_add_f32 v[58:59], v[58:59], v[180:181]
	v_cvt_pk_bf16_f32 v202, v60, v61
	v_cvt_pk_bf16_f32 v203, v62, v63
	v_cvt_pk_bf16_f32 v204, v56, v57
	v_cvt_pk_bf16_f32 v205, v58, v59
	global_store_dwordx4 v147, v[202:205], s[82:83] sc1
	v_lshlrev_b32_e32 v234, 16, v206
	v_and_b32_e32 v235, 0xffff0000, v206
	v_lshlrev_b32_e32 v236, 16, v207
	v_and_b32_e32 v237, 0xffff0000, v207
	v_lshlrev_b32_e32 v238, 16, v208
	v_and_b32_e32 v239, 0xffff0000, v208
	v_lshlrev_b32_e32 v180, 16, v209
	v_and_b32_e32 v181, 0xffff0000, v209
	v_pk_add_f32 v[52:53], v[52:53], v[234:235]
	v_pk_add_f32 v[54:55], v[54:55], v[236:237]
	v_pk_add_f32 v[48:49], v[48:49], v[238:239]
	v_pk_add_f32 v[50:51], v[50:51], v[180:181]
	v_cvt_pk_bf16_f32 v206, v52, v53
	v_cvt_pk_bf16_f32 v207, v54, v55
	v_cvt_pk_bf16_f32 v208, v48, v49
	v_cvt_pk_bf16_f32 v209, v50, v51
	global_store_dwordx4 v147, v[206:209], s[82:83] offset:256 sc1
	s_add_u32 s82, s82, s44
	s_addc_u32 s83, s83, 0
	s_waitcnt vmcnt(14)
	v_lshlrev_b32_e32 v234, 16, v210
	v_and_b32_e32 v235, 0xffff0000, v210
	v_lshlrev_b32_e32 v236, 16, v211
	v_and_b32_e32 v237, 0xffff0000, v211
	v_lshlrev_b32_e32 v238, 16, v212
	v_and_b32_e32 v239, 0xffff0000, v212
	v_lshlrev_b32_e32 v180, 16, v213
	v_and_b32_e32 v181, 0xffff0000, v213
	v_pk_add_f32 v[44:45], v[44:45], v[234:235]
	v_pk_add_f32 v[46:47], v[46:47], v[236:237]
	v_pk_add_f32 v[40:41], v[40:41], v[238:239]
	v_pk_add_f32 v[42:43], v[42:43], v[180:181]
	v_cvt_pk_bf16_f32 v210, v44, v45
	v_cvt_pk_bf16_f32 v211, v46, v47
	v_cvt_pk_bf16_f32 v212, v40, v41
	v_cvt_pk_bf16_f32 v213, v42, v43
	global_store_dwordx4 v147, v[210:213], s[82:83] sc1
	v_lshlrev_b32_e32 v234, 16, v214
	v_and_b32_e32 v235, 0xffff0000, v214
	v_lshlrev_b32_e32 v236, 16, v215
	v_and_b32_e32 v237, 0xffff0000, v215
	v_lshlrev_b32_e32 v238, 16, v216
	v_and_b32_e32 v239, 0xffff0000, v216
	v_lshlrev_b32_e32 v180, 16, v217
	v_and_b32_e32 v181, 0xffff0000, v217
	v_pk_add_f32 v[36:37], v[36:37], v[234:235]
	v_pk_add_f32 v[38:39], v[38:39], v[236:237]
	v_pk_add_f32 v[32:33], v[32:33], v[238:239]
	v_pk_add_f32 v[34:35], v[34:35], v[180:181]
	v_cvt_pk_bf16_f32 v214, v36, v37
	v_cvt_pk_bf16_f32 v215, v38, v39
	v_cvt_pk_bf16_f32 v216, v32, v33
	v_cvt_pk_bf16_f32 v217, v34, v35
	global_store_dwordx4 v147, v[214:217], s[82:83] offset:256 sc1
	s_add_u32 s82, s82, s44
	s_addc_u32 s83, s83, 0
	s_waitcnt vmcnt(14)
	v_lshlrev_b32_e32 v234, 16, v218
	v_and_b32_e32 v235, 0xffff0000, v218
	v_lshlrev_b32_e32 v236, 16, v219
	v_and_b32_e32 v237, 0xffff0000, v219
	v_lshlrev_b32_e32 v238, 16, v220
	v_and_b32_e32 v239, 0xffff0000, v220
	v_lshlrev_b32_e32 v180, 16, v221
	v_and_b32_e32 v181, 0xffff0000, v221
	v_pk_add_f32 v[28:29], v[28:29], v[234:235]
	v_pk_add_f32 v[30:31], v[30:31], v[236:237]
	v_pk_add_f32 v[24:25], v[24:25], v[238:239]
	v_pk_add_f32 v[26:27], v[26:27], v[180:181]
	v_cvt_pk_bf16_f32 v218, v28, v29
	v_cvt_pk_bf16_f32 v219, v30, v31
	v_cvt_pk_bf16_f32 v220, v24, v25
	v_cvt_pk_bf16_f32 v221, v26, v27
	global_store_dwordx4 v147, v[218:221], s[82:83] sc1
	v_lshlrev_b32_e32 v234, 16, v222
	v_and_b32_e32 v235, 0xffff0000, v222
	v_lshlrev_b32_e32 v236, 16, v223
	v_and_b32_e32 v237, 0xffff0000, v223
	v_lshlrev_b32_e32 v238, 16, v224
	v_and_b32_e32 v239, 0xffff0000, v224
	v_lshlrev_b32_e32 v180, 16, v225
	v_and_b32_e32 v181, 0xffff0000, v225
	v_pk_add_f32 v[20:21], v[20:21], v[234:235]
	v_pk_add_f32 v[22:23], v[22:23], v[236:237]
	v_pk_add_f32 v[16:17], v[16:17], v[238:239]
	v_pk_add_f32 v[18:19], v[18:19], v[180:181]
	v_cvt_pk_bf16_f32 v222, v20, v21
	v_cvt_pk_bf16_f32 v223, v22, v23
	v_cvt_pk_bf16_f32 v224, v16, v17
	v_cvt_pk_bf16_f32 v225, v18, v19
	global_store_dwordx4 v147, v[222:225], s[82:83] offset:256 sc1
	s_add_u32 s82, s82, s44
	s_addc_u32 s83, s83, 0
	s_waitcnt vmcnt(14)
	v_lshlrev_b32_e32 v234, 16, v226
	v_and_b32_e32 v235, 0xffff0000, v226
	v_lshlrev_b32_e32 v236, 16, v227
	v_and_b32_e32 v237, 0xffff0000, v227
	v_lshlrev_b32_e32 v238, 16, v228
	v_and_b32_e32 v239, 0xffff0000, v228
	v_lshlrev_b32_e32 v180, 16, v229
	v_and_b32_e32 v181, 0xffff0000, v229
	v_pk_add_f32 v[12:13], v[12:13], v[234:235]
	v_pk_add_f32 v[14:15], v[14:15], v[236:237]
	v_pk_add_f32 v[8:9], v[8:9], v[238:239]
	v_pk_add_f32 v[10:11], v[10:11], v[180:181]
	v_cvt_pk_bf16_f32 v226, v12, v13
	v_cvt_pk_bf16_f32 v227, v14, v15
	v_cvt_pk_bf16_f32 v228, v8, v9
	v_cvt_pk_bf16_f32 v229, v10, v11
	global_store_dwordx4 v147, v[226:229], s[82:83] sc1
	v_lshlrev_b32_e32 v234, 16, v230
	v_and_b32_e32 v235, 0xffff0000, v230
	v_lshlrev_b32_e32 v236, 16, v231
	v_and_b32_e32 v237, 0xffff0000, v231
	v_lshlrev_b32_e32 v238, 16, v232
	v_and_b32_e32 v239, 0xffff0000, v232
	v_lshlrev_b32_e32 v180, 16, v233
	v_and_b32_e32 v181, 0xffff0000, v233
	v_pk_add_f32 v[4:5], v[4:5], v[234:235]
	v_pk_add_f32 v[6:7], v[6:7], v[236:237]
	v_pk_add_f32 v[0:1], v[0:1], v[238:239]
	v_pk_add_f32 v[2:3], v[2:3], v[180:181]
	v_cvt_pk_bf16_f32 v230, v4, v5
	v_cvt_pk_bf16_f32 v231, v6, v7
	v_cvt_pk_bf16_f32 v232, v0, v1
	v_cvt_pk_bf16_f32 v233, v2, v3
	global_store_dwordx4 v147, v[230:233], s[82:83] offset:256 sc1

.LBB0_620:
	s_andn2_saveexec_b64 s[2:3], s[4:5]
	s_cbranch_execz .LBB0_640
	s_mov_b64 s[4:5], exec
	s_bitcmp1_b32 0x0, s86
	s_cbranch_scc1 .Lseam_nowb
	buffer_wbl2 sc1
